# pool-branch weight fold rewritten as f32 MFMA (v_mfma_f32_32x32x2_f32, f32 operands and accumulate): K=128 split over 4 wave pairs, partials reduced through LDS; replaces the L1-bandwidth-bound broadc
# speedup vs baseline: 1.0193x; 1.0083x over previous
; DI unsigned pack2(float a, float b) { f2_t v = {a, b}; bf2_t r = __builtin_convertvector(v, bf2_t); return __builtin_bit_cast(unsigned, r); }
; DI int get_tid(int wv) { int l; asm volatile("v_mbcnt_lo_u32_b32 %0, -1, 0\n\tv_mbcnt_hi_u32_b32 %0, -1, %0" : "=v"(l)); return wv * 64 + l; }
;     ...
;   const float* pool_w = pp->in[3] + (size_t)l * 4 * 128 * 128;
;   const float* pool_s = pp->in[4] + (size_t)l * 512;
;   for (int it = GRD - 1 - BID; it < (((mask >> 12) & 1) ? 16 * 16 : 0); it += GRD) {
;     const int k0 = (it >> 4) * 32, n0 = (it & 15) * 64;
;     const int tid = get_tid(WV);
;     const int n = n0 + (tid & 63), kb = k0 + (tid >> 6) * 4, g = kb >> 7;
;     float accv[4] = {0, 0, 0, 0};
;     const float* pw = pool_w + (size_t)(g * 128 + (kb & 127)) * 128;
; #pragma unroll 2
;     for (int d = 0; d < 128; d += 4) {
;       const f32x4 ps = *(const f32x4*)(pool_s + g * 128 + d);
;       float wv[4];
;       for (int q = 0; q < 4; ++q) wv[q] = ps[q] * w_branch[(long)(g * 128 + d + q) * DM + n];
;       for (int jj = 0; jj < 4; ++jj) {
;         const f32x4 p4 = *(const f32x4*)(pw + jj * 128 + d);
;         accv[jj] += p4[0] * wv[0] + p4[1] * wv[1] + p4[2] * wv[2] + p4[3] * wv[3];
;       }
;     }
;     uint2 o; o.x = pack2(accv[0], accv[1]); o.y = pack2(accv[2], accv[3]);
;     *(uint2*)(WB + (long)n * 512 + kb) = o;
;   }
.LBB0_409:
	s_barrier
	v_mbcnt_lo_u32_b32 v0, -1, 0
	v_mbcnt_hi_u32_b32 v0, -1, v0
	s_lshr_b32 s8, s3, 6
	s_and_b32 s9, s8, 1
	s_lshr_b32 s14, s8, 1
	s_and_b32 s15, s1, 0xffffffe0
	s_lshl_b32 s19, s17, 2
	s_and_b32 s19, s19, 0xf00
	s_and_b32 s21, s15, 0xffffff80
	s_lshl_b32 s22, s14, 7
	v_and_b32_e32 v14, 31, v0
	v_lshrrev_b32_e32 v15, 5, v0
	v_lshlrev_b32_e32 v17, 6, v15
	v_add_u32_e32 v16, s15, v14
	v_lshlrev_b32_e32 v16, 9, v16
	v_add3_u32 v16, v16, v17, s22
	s_lshl_b32 s23, s21, 2
	s_add_i32 s23, s23, s22
	v_add_u32_e32 v17, s23, v17
	v_lshlrev_b32_e32 v18, 16, v15
	v_lshl_add_u32 v18, v14, 2, v18
	s_lshl_b32 s26, s9, 7
	s_add_i32 s26, s26, s19
	v_add_u32_e32 v18, s26, v18
	s_lshl_b32 s27, s14, 5
	s_add_i32 s27, s27, s21
	s_lshl_b32 s27, s27, 12
	s_sub_u32 s24, s4, 0x7000
	s_subb_u32 s25, s5, 0
	s_add_u32 s24, s24, s27
	s_addc_u32 s25, s25, 0
	global_load_dwordx4 v[32:35], v16, s[12:13]
	global_load_dwordx4 v[36:39], v16, s[12:13] offset:16
	global_load_dwordx4 v[40:43], v16, s[12:13] offset:32
	global_load_dwordx4 v[44:47], v16, s[12:13] offset:48
	global_load_dwordx4 v[48:51], v17, s[10:11] offset:-16
	global_load_dwordx4 v[52:55], v17, s[10:11]
	global_load_dwordx4 v[56:59], v17, s[10:11] offset:16
	global_load_dwordx4 v[60:63], v17, s[10:11] offset:32
	global_load_dword v64, v18, s[24:25]
	s_add_u32 s24, s24, 0x1000
	s_addc_u32 s25, s25, 0
	global_load_dword v65, v18, s[24:25]
	s_add_u32 s24, s24, 0x1000
	s_addc_u32 s25, s25, 0
	global_load_dword v66, v18, s[24:25]
	s_add_u32 s24, s24, 0x1000
	s_addc_u32 s25, s25, 0
	global_load_dword v67, v18, s[24:25]
	s_add_u32 s24, s24, 0x1000
	s_addc_u32 s25, s25, 0
	global_load_dword v68, v18, s[24:25]
	s_add_u32 s24, s24, 0x1000
	s_addc_u32 s25, s25, 0
	global_load_dword v69, v18, s[24:25]
	s_add_u32 s24, s24, 0x1000
	s_addc_u32 s25, s25, 0
	global_load_dword v70, v18, s[24:25]
	s_add_u32 s24, s24, 0x1000
	s_addc_u32 s25, s25, 0
	global_load_dword v71, v18, s[24:25]
	s_add_u32 s24, s24, 0x1000
	s_addc_u32 s25, s25, 0
	global_load_dword v72, v18, s[24:25]
	s_add_u32 s24, s24, 0x1000
	s_addc_u32 s25, s25, 0
	global_load_dword v73, v18, s[24:25]
	s_add_u32 s24, s24, 0x1000
	s_addc_u32 s25, s25, 0
	global_load_dword v74, v18, s[24:25]
	s_add_u32 s24, s24, 0x1000
	s_addc_u32 s25, s25, 0
	global_load_dword v75, v18, s[24:25]
	s_add_u32 s24, s24, 0x1000
	s_addc_u32 s25, s25, 0
	global_load_dword v76, v18, s[24:25]
	s_add_u32 s24, s24, 0x1000
	s_addc_u32 s25, s25, 0
	global_load_dword v77, v18, s[24:25]
	s_add_u32 s24, s24, 0x1000
	s_addc_u32 s25, s25, 0
	global_load_dword v78, v18, s[24:25]
	s_add_u32 s24, s24, 0x1000
	s_addc_u32 s25, s25, 0
	global_load_dword v79, v18, s[24:25]
	s_lshl_b32 s28, s14, 6
	s_lshl_b32 s29, s9, 5
	s_add_i32 s28, s28, s29
	s_mul_i32 s28, s28, 0x90
	v_mul_u32_u24_e32 v19, 0x90, v14
	v_lshl_add_u32 v19, v15, 4, v19
	v_add_u32_e32 v19, s28, v19
	v_mul_u32_u24_e32 v20, 0x90, v0
	s_lshl_b32 s29, s8, 4
	v_add_u32_e32 v20, s29, v20
	s_lshl_b32 s29, s8, 2
	v_mov_b32_e32 v2, s29
	s_waitcnt vmcnt(0)
	v_pk_mul_f32 v[64:65], v[64:65], v[48:49]
	v_pk_mul_f32 v[66:67], v[66:67], v[50:51]
	v_pk_mul_f32 v[68:69], v[68:69], v[52:53]
	v_pk_mul_f32 v[70:71], v[70:71], v[54:55]
	v_pk_mul_f32 v[72:73], v[72:73], v[56:57]
	v_pk_mul_f32 v[74:75], v[74:75], v[58:59]
	v_pk_mul_f32 v[76:77], v[76:77], v[60:61]
	v_pk_mul_f32 v[78:79], v[78:79], v[62:63]
	s_nop 1
	v_mfma_f32_32x32x2_f32 v[80:95], v32, v64, 0
	v_mfma_f32_32x32x2_f32 v[80:95], v33, v65, v[80:95]
	v_mfma_f32_32x32x2_f32 v[80:95], v34, v66, v[80:95]
	v_mfma_f32_32x32x2_f32 v[80:95], v35, v67, v[80:95]
	v_mfma_f32_32x32x2_f32 v[80:95], v36, v68, v[80:95]
	v_mfma_f32_32x32x2_f32 v[80:95], v37, v69, v[80:95]
	v_mfma_f32_32x32x2_f32 v[80:95], v38, v70, v[80:95]
	v_mfma_f32_32x32x2_f32 v[80:95], v39, v71, v[80:95]
	v_mfma_f32_32x32x2_f32 v[80:95], v40, v72, v[80:95]
	v_mfma_f32_32x32x2_f32 v[80:95], v41, v73, v[80:95]
	v_mfma_f32_32x32x2_f32 v[80:95], v42, v74, v[80:95]
	v_mfma_f32_32x32x2_f32 v[80:95], v43, v75, v[80:95]
	v_mfma_f32_32x32x2_f32 v[80:95], v44, v76, v[80:95]
	v_mfma_f32_32x32x2_f32 v[80:95], v45, v77, v[80:95]
	v_mfma_f32_32x32x2_f32 v[80:95], v46, v78, v[80:95]
	v_mfma_f32_32x32x2_f32 v[80:95], v47, v79, v[80:95]
	s_nop 7
	s_nop 7
	s_nop 1
	ds_write_b128 v19, v[80:83]
	ds_write_b128 v19, v[84:87] offset:32
	ds_write_b128 v19, v[88:91] offset:64
	ds_write_b128 v19, v[92:95] offset:96
	s_waitcnt lgkmcnt(0)
	s_barrier
	ds_read_b128 v[24:27], v20
	ds_read_b128 v[28:31], v20 offset:9216
	ds_read_b128 v[96:99], v20 offset:18432
	ds_read_b128 v[100:103], v20 offset:27648
	s_waitcnt lgkmcnt(0)
	v_pk_add_f32 v[24:25], v[24:25], v[28:29]
	v_pk_add_f32 v[26:27], v[26:27], v[30:31]
	v_pk_add_f32 v[96:97], v[96:97], v[100:101]
	v_pk_add_f32 v[98:99], v[98:99], v[102:103]
	v_pk_add_f32 v[4:5], v[24:25], v[96:97]
	v_pk_add_f32 v[10:11], v[26:27], v[98:99]
	s_lshl_b32 s8, s0, 1
	s_lshl_b32 s9, s0, 6
	s_andn2_b32 s8, s8, 31
	s_and_b32 s9, s9, 0x3c0
	v_or_b32_e32 v0, s9, v0
	v_add_u32_e32 v2, s8, v2
	v_readlane_b32 s8, v255, 35
	v_lshlrev_b32_e32 v0, 10, v0
	v_readlane_b32 s9, v255, 36
	v_ashrrev_i32_e32 v3, 31, v2
	s_add_i32 s0, s0, s20
	v_lshl_add_u64 v[6:7], s[8:9], 0, v[0:1]
	s_add_i32 s1, s1, s16
	s_add_i32 s17, s17, s18
	v_cvt_pk_bf16_f32 v4, v4, v5
	v_cvt_pk_bf16_f32 v5, v10, v11
	v_lshl_add_u64 v[2:3], v[2:3], 1, v[6:7]
	s_cmpk_gt_i32 s0, 0xff
	global_store_dwordx2 v[2:3], v[4:5], off
	s_cbranch_scc0 .LBB0_409
